# v31 + P4 work remapped per row panel (pool-mix + gated norm of panel pm on the 8 WGs of merge tiles (pm,*)), P4->P5 grid barrier replaced by the 8-WG panel barrier
# speedup vs baseline: 1.0104x; 1.0054x over previous
; __device__ __forceinline__ u32x4 pack8(f32x4 v0, f32x4 v1) { u32x4 w; w.x = cvt_pk_bf16(v0[0], v0[1]); w.y = cvt_pk_bf16(v0[2], v0[3]); w.z = cvt_pk_bf16(v1[0], v1[1]); w.w = cvt_pk_bf16(v1[2], v1[3]); return w; }
; __device__ __forceinline__ void p3b_gnorm(Frame& F, const Args& a) {
;     const bf16_t *O = (const bf16_t*)(a.ws + WS_O), *SZD = (const bf16_t*)(a.ws + WS_SZD); bf16_t* Y = (bf16_t*)(a.ws + WS_Y); const float* w = a.in[9];
;     const bool split = F.G == 256;
;     if (split && F.vcu < 128) return;
;     const int gw = (split ? F.vcu - 128 : F.vcu) * NWAVES + F.wave, NGW = (split ? 128 : F.G) * NWAVES, lane = F.lane;
;     const f32x4 w0 = *(const f32x4*)(w + 8 * (lane & 15)), w1 = *(const f32x4*)(w + 8 * (lane & 15) + 4);
;     for (int r = gw; r < MTOK; r += NGW) {
;         pg8::u32x4 ov[4], zv[4];
; #pragma unroll
;         for (int j = 0; j < 4; ++j) { ov[j] = *(const pg8::u32x4*)(O + (size_t)r * DNW + 512 * j + 8 * lane); zv[j] = *(const pg8::u32x4*)(SZD + (size_t)r * DNW + 512 * j + 8 * lane); }
; #pragma unroll
;         for (int j = 0; j < 4; ++j) { f32x4 o0, o1, z0, z1; pg8::unpack8(ov[j], o0, o1); pg8::unpack8(zv[j], z0, z1);
;             float ss = (o0[0] * o0[0] + o0[1] * o0[1]) + (o0[2] * o0[2] + o0[3] * o0[3]) + (o1[0] * o1[0] + o1[1] * o1[1]) + (o1[2] * o1[2] + o1[3] * o1[3]);
;             ss += __shfl_xor(ss, 1); ss += __shfl_xor(ss, 2); ss += __shfl_xor(ss, 4); ss += __shfl_xor(ss, 8);
;             const float rs = rsqrtf(ss * (1.f / HD) + EPS);
;             *(pg8::u32x4*)(Y + (size_t)r * YLD + 1024 + 512 * j + 8 * lane) = pg8::pack8(o0 * rs * w0 * z0, o1 * rs * w1 * z1); }
;     }
.LBB0_850:
	s_cmp_gt_i32 s4, 4
	s_cselect_b64 s[0:1], -1, 0
	s_cmp_lt_i32 s5, 5
	s_cselect_b64 s[2:3], -1, 0
	s_or_b64 s[0:1], s[0:1], s[2:3]
	s_and_b64 vcc, exec, s[0:1]
	s_cbranch_vccnz .LBB0_913
	v_readlane_b32 s0, v255, 3
	s_cmpk_lt_i32 s0, 0x80
	s_cselect_b64 s[8:9], -1, 0
	s_bitcmp0_b32 s0, 4
	s_cselect_b64 s[2:3], -1, 0
	v_readlane_b32 s0, v255, 9
	v_readlane_b32 s1, v255, 10
	s_cmp_lg_u32 s0, 0
	s_cselect_b64 s[8:9], s[2:3], s[8:9]
	s_and_b64 s[0:1], s[0:1], s[8:9]
	s_and_b64 vcc, exec, s[0:1]
	s_cbranch_vccnz .LBB0_855
	v_readlane_b32 s0, v255, 3
	s_lshl_b32 s2, s0, 3
	s_lshr_b32 s3, s0, 5
	s_lshl_b32 s3, s3, 2
	s_and_b32 s4, s0, 3
	s_add_i32 s3, s3, s4
	s_lshl_b32 s3, s3, 8
	s_bfe_u32 s4, s0, 0x20002
	s_lshl_b32 s4, s4, 6
	s_add_i32 s3, s3, s4
	s_add_i32 s4, s2, s78
	s_add_i32 s5, s78, 0x1fc0
	v_readlane_b32 s0, v255, 9
	v_readlane_b32 s1, v255, 10
	s_and_b64 s[0:1], s[0:1], exec
	s_cselect_b32 s1, s3, s2
	s_cselect_b32 s0, s5, s4
	v_readlane_b32 s2, v255, 9
	v_readlane_b32 s3, v255, 10
	s_cmpk_gt_i32 s0, 0x1fff
	s_cbranch_scc1 .LBB0_855
	v_lshlrev_b32_e32 v1, 5, v254
	v_and_b32_e32 v1, 0x1e0, v1
	global_load_dwordx4 v[2:5], v1, s[14:15] offset:16
	global_load_dwordx4 v[6:9], v1, s[14:15]
	s_lshl_b32 s4, s52, 3
	v_mbcnt_lo_u32_b32 v1, -1, 0
	s_and_b64 s[2:3], s[2:3], exec
	s_waitcnt vmcnt(0)
	v_mbcnt_hi_u32_b32 v10, -1, v1
	s_cselect_b32 s14, 8, s4
	v_and_b32_e32 v11, 64, v10
	s_ashr_i32 s3, s1, 31
	v_xor_b32_e32 v1, 1, v10
	v_add_u32_e32 v11, 64, v11
	s_add_u32 s2, s78, s1
	v_cmp_lt_i32_e32 vcc, v1, v11
	v_xor_b32_e32 v12, 2, v10
	s_addc_u32 s3, 0, s3
	v_cndmask_b32_e32 v1, v10, v1, vcc
	v_cmp_lt_i32_e32 vcc, v12, v11
	s_lshl_b64 s[4:5], s[2:3], 12
	s_add_u32 s16, s26, s4
	v_cndmask_b32_e32 v12, v10, v12, vcc
	v_lshlrev_b32_e32 v18, 2, v12
	v_xor_b32_e32 v12, 4, v10
	s_addc_u32 s17, s27, s5
	s_ashr_i32 s15, s14, 31
	s_mul_i32 s1, s3, 0x1800
	s_mul_hi_u32 s3, s2, 0x1800
	v_cmp_lt_i32_e32 vcc, v12, v11
	s_lshl_b64 s[18:19], s[14:15], 12
	s_add_i32 s3, s3, s1
	s_mul_i32 s1, s2, 0x1800
	v_cndmask_b32_e32 v12, v10, v12, vcc
	s_add_u32 s1, s26, s1
	v_lshlrev_b32_e32 v19, 2, v12
	v_xor_b32_e32 v12, 8, v10
	s_addc_u32 s2, s27, s3
	v_cmp_lt_i32_e32 vcc, v12, v11
	s_add_u32 s20, s1, 0xec01000
	s_addc_u32 s21, s2, 0
	v_cndmask_b32_e32 v10, v10, v12, vcc
	s_mov_b32 s2, 0x358637bd
	v_lshlrev_b32_e32 v1, 2, v1
	v_lshlrev_b32_e32 v20, 2, v10
	v_lshlrev_b32_e32 v10, 4, v254
	v_mov_b32_e32 v11, 0
	s_mul_hi_i32 s1, s14, 0x1800
	s_mul_i32 s10, s14, 0x1800
	s_brev_b32 s28, 60
	v_mov_b64_e32 v[12:13], s[2:3]
	s_mov_b32 s11, 0x800000

; #define PG8_STAGE(bufoff, gbase, voff) do { _Pragma("unroll") for (int _i = 0; _i < 2; ++_i) \
;         __builtin_amdgcn_global_load_lds((const unsigned*)((const char*)(gbase) + (voff)[_i]), (PG8_LAS unsigned*)(lds + (bufoff) + ldsw + _i * 8192), 16, 0, 0); } while (0)
; #define PG8_WAIT_V(n) asm volatile("s_waitcnt vmcnt(" #n ")" ::: "memory")
; template <class Epi, class Sched, bool ALIGN_EPI>
; __device__ __forceinline__ void gemm_phase(PG8_LAS unsigned char* lds, const Gemm g, const Sched& S, const Epi& E) {
;     const int tid = threadIdx.x, wid = __builtin_amdgcn_readfirstlane(tid >> 6), lane = tid & 63, wr = wid >> 2, wc = wid & 3, fr = lane & 15, fq = lane >> 4;
;     const int lda = g.lda, ldb = g.ldb;
;     unsigned voffA[2], voffB[2];
; #pragma unroll
;     for (int i = 0; i < 2; ++i) { int R, C; stage_rc(tid * 16 + i * 8192, R, C); const int Rb = Epi::PERM ? ((R & ~31) + perm32(R & 31)) : R;
;         voffA[i] = (unsigned)(R * lda + C) * 2u; voffB[i] = (unsigned)(Rb * ldb + C) * 2u; }
;     const size_t kstep = (size_t)(BK * 2);
;     const size_t hstepA = (size_t)HALF * lda * 2, hstepB = (size_t)HALF * ldb * 2;
;     const unsigned ldsw = (unsigned)wid * 1024u;
;     const int aoff = lds_byte(wr * 64 + fr, fq * 8), boff = lds_byte(wc * 32 + fr, fq * 8);
;     ...
;     Unit cur, nxt; int ui = 0;
;     if (!S.next(0, cur)) return;
;     f32x4 acc[2][2][4][2];
;     if constexpr (Epi::HAS_INIT) E.init(acc, cur, wr, wc, fr, fq);
;     else {
; #pragma unroll
;     for (int a = 0; a < 2; ++a)
; #pragma unroll
;         for (int b = 0; b < 2; ++b)
; #pragma unroll
;             for (int m = 0; m < 4; ++m)
; #pragma unroll
;                 for (int n = 0; n < 2; ++n) acc[a][b][m][n] = (f32x4){0.f, 0.f, 0.f, 0.f};
;     }
;     bf16x8 At[4][2], B0[2][2], B1[2][2];
;     const char* cA = PG8_UA(cur); const char* cB = PG8_UB(cur);
;     if constexpr (Sched::GATED) { S.gate(cur, wid == 0); __builtin_amdgcn_s_barrier(); }
;     PG8_STAGE(PG8_SB(0, 0), cB, voffB); PG8_STAGE(PG8_SB(0, 1), cB + hstepB, voffB); PG8_STAGE(PG8_SA(0, 0), cA, voffA); PG8_STAGE(PG8_SA(0, 1), cA + hstepA, voffA);
;     if (wr == 1) PG8_BAR;
;     PG8_WAIT_V(2); PG8_BAR;
;     PG8_STAGE(PG8_SB(1, 0), cB + kstep, voffB); PG8_STAGE(PG8_SA(1, 0), cA + kstep, voffA); PG8_STAGE(PG8_SB(1, 1), cB + hstepB + kstep, voffB);
;     PG8_WAIT_V(6); PG8_BAR;
.LBB0_855:
	s_andn2_b64 vcc, exec, s[8:9]
	v_readfirstlane_b32 s0, v0
	s_cbranch_vccnz .LBB0_863
	s_add_u32 s1, s26, 0x19380000
	v_lshrrev_b32_e32 v1, 5, v0
	s_waitcnt vmcnt(0)
	v_lshrrev_b32_e32 v3, 1, v0
	s_addc_u32 s10, s27, 0
	v_and_b32_e32 v1, 4, v1
	v_bfe_u32 v2, v0, 2, 2
	v_and_b32_e32 v3, 24, v3
	s_add_u32 s11, s26, 0xaa00000
	v_readlane_b32 s2, v255, 3
	v_or3_b32 v1, v1, v2, v3
	v_lshlrev_b32_e32 v2, 4, v0
	v_bfe_u32 v3, v0, 3, 25
	v_and_b32_e32 v5, 32, v0
	s_addc_u32 s33, s27, 0
	s_lshr_b32 s3, s2, 5
	s_lshl_b32 s3, s3, 4
	s_and_b32 s5, s2, 3
	s_lshl_b32 s5, s5, 2
	s_add_i32 s3, s3, s5
	s_bfe_u32 s5, s2, 0x20002
	s_add_i32 s3, s3, s5
	v_readlane_b32 s5, v255, 9
	s_cmp_lg_u32 s5, 0
	s_cselect_b32 s2, s3, s2
	s_ashr_i32 s28, s2, 2
	s_and_b32 s68, s2, 3
	v_or_b32_e32 v3, 64, v3
	s_movk_i32 s2, 0x60
	v_bitop3_b32 v2, v2, v5, 48 bitop3:0x6c
	v_and_or_b32 v4, v3, s2, v1
	v_and_or_b32 v2, v0, 64, v2
	s_lshr_b32 s5, s0, 6
	v_readlane_b32 s3, v255, 4
	v_lshl_or_b32 v122, v4, 9, v2
	v_bfe_u32 v4, v0, 2, 4
	s_movk_i32 s2, 0x70
	s_ashr_i32 s29, s28, 31
	s_lshr_b32 s4, s0, 8
	s_lshl_b32 s16, s5, 10
	s_lshl_b32 s6, s68, 9
	v_and_or_b32 v3, v3, s2, v4
	s_lshl_b64 s[2:3], s[28:29], 19
	s_add_u32 s7, s1, s2
	s_addc_u32 s8, s10, s3
	s_lshl_b32 s2, s68, 17
	v_lshl_or_b32 v124, v3, 11, v2
	v_lshrrev_b32_e32 v3, 3, v0
	s_add_u32 s40, s11, s2
	v_and_or_b32 v1, v3, 32, v1
	s_addc_u32 s41, s33, 0
	s_add_i32 s29, s16, 0
	v_lshl_or_b32 v126, v1, 9, v2
	s_add_i32 m0, s29, 0x10000
	v_and_or_b32 v1, v3, 48, v4
	global_load_lds_dwordx4 v126, s[40:41]
	s_add_i32 m0, s29, 0x12000
	s_add_u32 s2, s40, 0x10000
	global_load_lds_dwordx4 v122, s[40:41]
	s_addc_u32 s3, s41, 0
	s_add_i32 m0, s29, 0x14000
	v_lshl_or_b32 v128, v1, 11, v2
	global_load_lds_dwordx4 v126, s[2:3]
	s_add_i32 m0, s29, 0x16000
	s_add_u32 s38, s7, s6
	s_addc_u32 s39, s8, 0
	s_add_i32 s34, s29, 0x2000
	global_load_lds_dwordx4 v122, s[2:3]
	s_mov_b32 m0, s29
	s_add_u32 s2, s38, 0x40000
	global_load_lds_dwordx4 v128, s[38:39]
	s_mov_b32 m0, s34
	s_addc_u32 s3, s39, 0
	s_add_i32 s35, s29, 0x4000
	global_load_lds_dwordx4 v124, s[38:39]
	s_mov_b32 m0, s35
	s_add_i32 s44, s29, 0x6000
	global_load_lds_dwordx4 v128, s[2:3]
	s_mov_b32 m0, s44
	v_mov_b32_e32 v127, 0
	global_load_lds_dwordx4 v124, s[2:3]
	v_mov_b32_e32 v123, v127
	v_mov_b32_e32 v129, v127
	v_mov_b32_e32 v125, v127
	s_mov_b32 s7, 0
	v_lshl_add_u64 v[8:9], s[40:41], 0, v[126:127]
	v_lshl_add_u64 v[6:7], s[40:41], 0, v[122:123]
	v_lshl_add_u64 v[4:5], s[38:39], 0, v[128:129]
	v_lshl_add_u64 v[2:3], s[38:39], 0, v[124:125]
	s_cmp_lg_u32 s4, 1
	s_movk_i32 s45, 0x2000
	s_cbranch_scc1 .LBB0_858
	s_barrier
.LBB0_858:
	s_add_u32 s18, s26, 0xec00000
	s_addc_u32 s19, s27, 0
	s_add_u32 s2, s26, 0xbb80000
	s_addc_u32 s3, s27, 0
	s_and_b32 s6, s5, 3
	s_lshl_b32 s46, s4, 6
	s_lshl_b32 s14, s4, 13
	s_mov_b64 s[4:5], 0x80
	s_add_i32 m0, s29, 0x18000
	v_lshl_add_u64 v[8:9], v[8:9], 0, s[4:5]
	s_lshl_b32 s47, s6, 5
	s_lshl_b32 s15, s6, 12
	s_waitcnt vmcnt(2)
	s_barrier
	global_load_lds_dwordx4 v[8:9], off
	v_lshl_add_u64 v[6:7], v[6:7], 0, s[4:5]
	s_add_i32 m0, s29, 0x1a000
	s_add_i32 s48, s29, 0x8000
	s_add_i32 s49, s29, 0xa000
	global_load_lds_dwordx4 v[6:7], off
	v_lshl_add_u64 v[4:5], v[4:5], 0, s[4:5]
	s_mov_b32 m0, s48
	s_add_u32 s8, s40, 0x10080
	global_load_lds_dwordx4 v[4:5], off
	v_lshl_add_u64 v[2:3], v[2:3], 0, s[4:5]
	s_mov_b32 m0, s49
	s_addc_u32 s9, s41, 0
	global_load_lds_dwordx4 v[2:3], off
	s_add_i32 m0, s29, 0x1c000
	v_lshl_add_u64 v[2:3], s[8:9], 0, v[126:127]
	global_load_lds_dwordx4 v[2:3], off
	v_lshl_add_u64 v[2:3], s[8:9], 0, v[122:123]
	s_add_i32 m0, s29, 0x1e000
	v_and_b32_e32 v1, 48, v0
	global_load_lds_dwordx4 v[2:3], off
	v_lshlrev_b32_e32 v2, 6, v0
	s_movk_i32 s8, 0x3c0
	v_and_or_b32 v1, v2, s8, v1
	v_lshlrev_b32_e32 v2, 2, v0
	v_and_b32_e32 v2, 32, v2
	v_bitop3_b32 v3, v1, s14, v2 bitop3:0xde
	v_bitop3_b32 v2, s15, v1, v2 bitop3:0xf6
	s_waitcnt vmcnt(6)
	s_lshl_b32 s6, s6, 4
	s_add_i32 s53, 0, 0x10000
	s_add_i32 s58, 0, 0x14000
	s_add_i32 s60, 0, 0x18000
	s_add_i32 s62, 0, 0x1c000
	s_or_b32 s6, s6, s46
	v_add_u32_e32 v1, s53, v2
	v_add_u32_e32 v136, s58, v2
	s_add_i32 s53, s53, s16
	s_add_i32 s58, s58, s16
	v_add_u32_e32 v138, s60, v2
	v_add_u32_e32 v139, s62, v2
	s_add_i32 s60, s60, s16
	s_add_i32 s62, s62, s16
	v_readlane_b32 s16, v255, 3
	s_lshl_b64 s[6:7], s[6:7], 10
	v_add_u32_e32 v137, 0, v3
	s_add_i32 s50, s29, 0xc000
	s_add_i32 s51, s29, 0xe000
	s_mov_b64 s[8:9], 0x100
	s_add_i32 s54, s53, 0x2000
	s_mov_b64 s[14:15], 0x180
	s_movk_i32 s55, 0x1800
	v_mov_b64_e32 v[130:131], s[18:19]
	s_movk_i32 s56, 0x1000
	s_movk_i32 s57, 0x3000
	s_add_i32 s59, s58, 0x2000
	s_add_i32 s61, s60, 0x2000
	s_add_i32 s63, s62, 0x2000
	s_lshl_b32 s64, s28, 2
	s_or_b32 s64, s64, s68
	s_barrier
	v_readlane_b32 s17, v255, 4

; __device__ __forceinline__ unsigned xb_ld(unsigned* p)              { return __hip_atomic_load(p, __ATOMIC_RELAXED, __HIP_MEMORY_SCOPE_AGENT); }
; __device__ __forceinline__ unsigned xb_add(unsigned* p, unsigned v) { return __hip_atomic_fetch_add(p, v, __ATOMIC_RELAXED, __HIP_MEMORY_SCOPE_AGENT); }
; #define XB_SPIN(cond, bar) do { unsigned _sp = 0; while (cond) { __builtin_amdgcn_s_sleep(1); \
;     if ((++_sp & 255u) == 0u) { if (xb_ld(&(bar)[XB_TMO])) break; if (_sp > XB_SPIN_CAP) { atomicAdd(&(bar)[XB_TMO], 1u); break; } } } } while (0)
; __device__ __forceinline__ void xcd_barrier(const XcdBarrier& b) {
;     asm volatile("s_waitcnt vmcnt(0)" ::: "memory");
;     __syncthreads();
;     if (threadIdx.x == 0) {
;         unsigned* bar = b.bar;
;         __builtin_amdgcn_s_waitcnt(0);
;         unsigned nloc = b.st[0], nx = b.st[1];
;         if (nloc == 0u) { xcd_barrier_complete(bar, b.x, nloc, nx); b.st[0] = nloc; b.st[1] = nx; }
;         const unsigned old = xb_add(&bar[XB_XSUB(b.x)], 1u);
;         const unsigned gen = old / nloc;
;         if (old + 1u == (gen + 1u) * nloc) {
;             __builtin_amdgcn_fence(__ATOMIC_RELEASE, "agent");
;             asm volatile("s_waitcnt vmcnt(0)" ::: "memory");
;             const unsigned og = xb_add(&bar[XB_TOP], 1u);
;             const unsigned tg = og / nx;
;             if (og + 1u == (tg + 1u) * nx) xb_add(&bar[XB_TOPGEN], 1u);
;             else XB_SPIN(xb_ld(&bar[XB_TOPGEN]) == tg, bar);
;             __builtin_amdgcn_fence(__ATOMIC_ACQUIRE, "agent");
;             xb_add(&bar[XB_XGEN(b.x)], 1u);
;             asm volatile("s_waitcnt vmcnt(0)" ::: "memory");
;         } else {
;             XB_SPIN(xb_ld(&bar[XB_XGEN(b.x)]) == gen, bar);
;             __builtin_amdgcn_fence(__ATOMIC_ACQUIRE, "agent");
;             asm volatile("s_waitcnt vmcnt(0)" ::: "memory");
;         }
;     }
;     __syncthreads();
; }
.LBB0_863:
	v_readlane_b32 s4, v255, 5
	v_readlane_b32 s5, v255, 6
	s_cmp_lt_u32 s5, 6
	s_cbranch_scc1 .LBB0_913
	v_readlane_b32 s0, v255, 9
	s_cmp_eq_u32 s0, 0
	s_cbranch_scc1 .Lgc_grid
	v_readfirstlane_b32 s0, v0
	s_cmp_ge_u32 s0, 64
	s_cbranch_scc1 .Lgc_nold
	v_readlane_b32 s0, v255, 2
	s_and_b32 s1, s0, 7
	s_lshr_b32 s0, s0, 3
	s_and_b32 s0, s0, 3
	s_lshl_b32 s1, s1, 2
	s_add_i32 s0, s0, s1
	s_lshl_b32 s0, s0, 5
	s_add_i32 s0, s0, 0x51000
	v_and_b32_e32 v1, 7, v0
	v_lshl_add_u32 v1, v1, 2, s0
	global_load_dword v1, v1, s[26:27] sc1
.Lgc_nold:
	s_waitcnt vmcnt(0)
	s_barrier
	v_readlane_b32 s4, v1, 0
	v_cmp_ne_u32_e32 vcc, s4, v1
	s_and_b32 s5, vcc_lo, 0xff
	s_cmp_eq_u32 s5, 0
	s_cselect_b32 s5, 1, 0
	s_cmp_lg_u32 s4, 0
	s_cselect_b32 s98, s5, 0
	v_cmp_eq_u32_e32 vcc, 0, v0
	s_and_saveexec_b64 s[2:3], vcc
	s_cbranch_execz .LBB0_912
	s_cmp_eq_u32 s98, 1
	s_cbranch_scc1 .Lgc_noflush
	buffer_wbl2 sc1
	s_waitcnt vmcnt(0)
.Lgc_noflush:
	v_readlane_b32 s0, v255, 2
	s_and_b32 s1, s0, 7
	s_lshr_b32 s0, s0, 3
	s_and_b32 s0, s0, 3
	s_lshl_b32 s1, s1, 2
	s_add_i32 s0, s0, s1
	s_lshl_b32 s0, s0, 8
	s_add_i32 s0, s0, 0x52000
	s_add_u32 s4, s26, s0
	s_addc_u32 s5, s27, 0
	v_mov_b32_e32 v1, 0
	v_mov_b32_e32 v2, 1
	global_atomic_add v1, v2, s[4:5]
	s_mov_b32 s6, 0
